# first grid barrier: census of the 16 per-XCC counters issued as 16 loads in flight + one wait (was 16 dependent sc1 round trips)
# speedup vs baseline: 1.0029x; 1.0029x over previous
.LBB0_511:
	v_readlane_b32 s2, v253, 14
	v_readlane_b32 s3, v253, 15
	s_mov_b64 s[38:39], -1
	s_mov_b64 s[40:41], -1
	s_nop 4
	global_load_dword v0, v3, s[2:3] sc1
	global_load_dword v1, v3, s[2:3] offset:256 sc1
	global_load_dword v2, v3, s[2:3] offset:512 sc1
	global_load_dword v4, v3, s[2:3] offset:768 sc1
	global_load_dword v5, v3, s[2:3] offset:1024 sc1
	global_load_dword v6, v3, s[2:3] offset:1280 sc1
	global_load_dword v7, v3, s[2:3] offset:1536 sc1
	global_load_dword v8, v3, s[2:3] offset:1792 sc1
	global_load_dword v9, v3, s[2:3] offset:2048 sc1
	global_load_dword v10, v3, s[2:3] offset:2304 sc1
	global_load_dword v11, v3, s[2:3] offset:2560 sc1
	global_load_dword v12, v3, s[2:3] offset:2816 sc1
	global_load_dword v13, v3, s[2:3] offset:3072 sc1
	global_load_dword v14, v3, s[2:3] offset:3328 sc1
	global_load_dword v15, v3, s[2:3] offset:3584 sc1
	global_load_dword v16, v3, s[2:3] offset:3840 sc1
	s_waitcnt vmcnt(0)
	v_add_u32_e32 v17, v1, v0
	v_add_u32_e32 v17, v17, v2
	v_add_u32_e32 v17, v17, v4
	v_add_u32_e32 v17, v17, v5
	v_add_u32_e32 v17, v17, v6
	v_add_u32_e32 v17, v17, v7
	v_add_u32_e32 v17, v17, v8
	v_add_u32_e32 v17, v17, v9
	v_add_u32_e32 v17, v17, v10
	v_add_u32_e32 v17, v17, v11
	v_add_u32_e32 v17, v17, v12
	v_add_u32_e32 v17, v17, v13
	v_add_u32_e32 v17, v17, v14
	v_add_u32_e32 v17, v17, v15
	v_add_u32_e32 v17, v17, v16
	v_cmp_eq_u32_e32 vcc, s20, v17
	s_cbranch_vccnz .LBB0_510
	s_and_b32 s22, s21, 0xff
	s_cmp_eq_u32 s22, 0
	s_mov_b64 s[42:43], -1
	s_sleep 1
	s_cbranch_scc0 .LBB0_515
	v_readlane_b32 s2, v253, 12
	v_readlane_b32 s3, v253, 13
	s_nop 4
	global_load_dword v17, v3, s[2:3] sc1
	s_waitcnt vmcnt(0)
	v_cmp_eq_u32_e32 vcc, 0, v17
	s_cbranch_vccnz .LBB0_517
	s_mov_b64 s[42:43], 0
